# mixc LayerNorm statistics: all 96 channel loads of the token column issued back to back (one exposed latency instead of eight), same accumulation order
# speedup vs baseline: 1.0052x; 1.0052x over previous
; DI float bf2f(u16 v) { return __uint_as_float(((unsigned)v) << 16); }
; DI void phase_mixc(const Prm& p, unsigned char* smem_raw, int l, int& base) {
;     ...
;       const int q = tid & 127, qf = tid >> 7;
;       float s = 0.f, ss = 0.f;
;       const u16* src = p.cvT + (size_t)(qf * 96) * TBP + tok0 + q;
;       for (int c = 0; c < 96; ++c) { const float v = bf2f(src[(size_t)c * TBP]); s += v; ss += v * v; }
.LBB0_2003:
	v_mov_b32_e32 v4, v2
	v_mov_b32_e32 v5, v3
	global_load_ushort v100, v[4:5], off
	v_add_co_u32_e32 v4, vcc, 0x8080, v4
	s_nop 1
	v_addc_co_u32_e32 v5, vcc, 0, v5, vcc
	global_load_ushort v101, v[4:5], off
	v_add_co_u32_e32 v4, vcc, 0x8080, v4
	s_nop 1
	v_addc_co_u32_e32 v5, vcc, 0, v5, vcc
	global_load_ushort v102, v[4:5], off
	v_add_co_u32_e32 v4, vcc, 0x8080, v4
	s_nop 1
	v_addc_co_u32_e32 v5, vcc, 0, v5, vcc
	global_load_ushort v103, v[4:5], off
	v_add_co_u32_e32 v4, vcc, 0x8080, v4
	s_nop 1
	v_addc_co_u32_e32 v5, vcc, 0, v5, vcc
	global_load_ushort v104, v[4:5], off
	v_add_co_u32_e32 v4, vcc, 0x8080, v4
	s_nop 1
	v_addc_co_u32_e32 v5, vcc, 0, v5, vcc
	global_load_ushort v105, v[4:5], off
	v_add_co_u32_e32 v4, vcc, 0x8080, v4
	s_nop 1
	v_addc_co_u32_e32 v5, vcc, 0, v5, vcc
	global_load_ushort v106, v[4:5], off
	v_add_co_u32_e32 v4, vcc, 0x8080, v4
	s_nop 1
	v_addc_co_u32_e32 v5, vcc, 0, v5, vcc
	global_load_ushort v107, v[4:5], off
	v_add_co_u32_e32 v4, vcc, 0x8080, v4
	s_nop 1
	v_addc_co_u32_e32 v5, vcc, 0, v5, vcc
	global_load_ushort v108, v[4:5], off
	v_add_co_u32_e32 v4, vcc, 0x8080, v4
	s_nop 1
	v_addc_co_u32_e32 v5, vcc, 0, v5, vcc
	global_load_ushort v109, v[4:5], off
	v_add_co_u32_e32 v4, vcc, 0x8080, v4
	s_nop 1
	v_addc_co_u32_e32 v5, vcc, 0, v5, vcc
	global_load_ushort v110, v[4:5], off
	v_add_co_u32_e32 v4, vcc, 0x8080, v4
	s_nop 1
	v_addc_co_u32_e32 v5, vcc, 0, v5, vcc
	global_load_ushort v111, v[4:5], off
	v_add_co_u32_e32 v4, vcc, 0x8080, v4
	s_nop 1
	v_addc_co_u32_e32 v5, vcc, 0, v5, vcc
	global_load_ushort v112, v[4:5], off
	v_add_co_u32_e32 v4, vcc, 0x8080, v4
	s_nop 1
	v_addc_co_u32_e32 v5, vcc, 0, v5, vcc
	global_load_ushort v113, v[4:5], off
	v_add_co_u32_e32 v4, vcc, 0x8080, v4
	s_nop 1
	v_addc_co_u32_e32 v5, vcc, 0, v5, vcc
	global_load_ushort v114, v[4:5], off
	v_add_co_u32_e32 v4, vcc, 0x8080, v4
	s_nop 1
	v_addc_co_u32_e32 v5, vcc, 0, v5, vcc
	global_load_ushort v115, v[4:5], off
	v_add_co_u32_e32 v4, vcc, 0x8080, v4
	s_nop 1
	v_addc_co_u32_e32 v5, vcc, 0, v5, vcc
	global_load_ushort v116, v[4:5], off
	v_add_co_u32_e32 v4, vcc, 0x8080, v4
	s_nop 1
	v_addc_co_u32_e32 v5, vcc, 0, v5, vcc
	global_load_ushort v117, v[4:5], off
	v_add_co_u32_e32 v4, vcc, 0x8080, v4
	s_nop 1
	v_addc_co_u32_e32 v5, vcc, 0, v5, vcc
	global_load_ushort v118, v[4:5], off
	v_add_co_u32_e32 v4, vcc, 0x8080, v4
	s_nop 1
	v_addc_co_u32_e32 v5, vcc, 0, v5, vcc
	global_load_ushort v119, v[4:5], off
	v_add_co_u32_e32 v4, vcc, 0x8080, v4
	s_nop 1
	v_addc_co_u32_e32 v5, vcc, 0, v5, vcc
	global_load_ushort v120, v[4:5], off
	v_add_co_u32_e32 v4, vcc, 0x8080, v4
	s_nop 1
	v_addc_co_u32_e32 v5, vcc, 0, v5, vcc
	global_load_ushort v121, v[4:5], off
	v_add_co_u32_e32 v4, vcc, 0x8080, v4
	s_nop 1
	v_addc_co_u32_e32 v5, vcc, 0, v5, vcc
	global_load_ushort v122, v[4:5], off
	v_add_co_u32_e32 v4, vcc, 0x8080, v4
	s_nop 1
	v_addc_co_u32_e32 v5, vcc, 0, v5, vcc
	global_load_ushort v123, v[4:5], off
	v_add_co_u32_e32 v4, vcc, 0x8080, v4
	s_nop 1
	v_addc_co_u32_e32 v5, vcc, 0, v5, vcc
	global_load_ushort v124, v[4:5], off
	v_add_co_u32_e32 v4, vcc, 0x8080, v4
	s_nop 1
	v_addc_co_u32_e32 v5, vcc, 0, v5, vcc
	global_load_ushort v125, v[4:5], off
	v_add_co_u32_e32 v4, vcc, 0x8080, v4
	s_nop 1
	v_addc_co_u32_e32 v5, vcc, 0, v5, vcc
	global_load_ushort v126, v[4:5], off
	v_add_co_u32_e32 v4, vcc, 0x8080, v4
	s_nop 1
	v_addc_co_u32_e32 v5, vcc, 0, v5, vcc
	global_load_ushort v127, v[4:5], off
	v_add_co_u32_e32 v4, vcc, 0x8080, v4
	s_nop 1
	v_addc_co_u32_e32 v5, vcc, 0, v5, vcc
	global_load_ushort v128, v[4:5], off
	v_add_co_u32_e32 v4, vcc, 0x8080, v4
	s_nop 1
	v_addc_co_u32_e32 v5, vcc, 0, v5, vcc
	global_load_ushort v129, v[4:5], off
	v_add_co_u32_e32 v4, vcc, 0x8080, v4
	s_nop 1
	v_addc_co_u32_e32 v5, vcc, 0, v5, vcc
	global_load_ushort v130, v[4:5], off
	v_add_co_u32_e32 v4, vcc, 0x8080, v4
	s_nop 1
	v_addc_co_u32_e32 v5, vcc, 0, v5, vcc
	global_load_ushort v131, v[4:5], off
	v_add_co_u32_e32 v4, vcc, 0x8080, v4
	s_nop 1
	v_addc_co_u32_e32 v5, vcc, 0, v5, vcc
	global_load_ushort v132, v[4:5], off
	v_add_co_u32_e32 v4, vcc, 0x8080, v4
	s_nop 1
	v_addc_co_u32_e32 v5, vcc, 0, v5, vcc
	global_load_ushort v133, v[4:5], off
	v_add_co_u32_e32 v4, vcc, 0x8080, v4
	s_nop 1
	v_addc_co_u32_e32 v5, vcc, 0, v5, vcc
	global_load_ushort v134, v[4:5], off
	v_add_co_u32_e32 v4, vcc, 0x8080, v4
	s_nop 1
	v_addc_co_u32_e32 v5, vcc, 0, v5, vcc
	global_load_ushort v135, v[4:5], off
	v_add_co_u32_e32 v4, vcc, 0x8080, v4
	s_nop 1
	v_addc_co_u32_e32 v5, vcc, 0, v5, vcc
	global_load_ushort v136, v[4:5], off
	v_add_co_u32_e32 v4, vcc, 0x8080, v4
	s_nop 1
	v_addc_co_u32_e32 v5, vcc, 0, v5, vcc
	global_load_ushort v137, v[4:5], off
	v_add_co_u32_e32 v4, vcc, 0x8080, v4
	s_nop 1
	v_addc_co_u32_e32 v5, vcc, 0, v5, vcc
	global_load_ushort v138, v[4:5], off
	v_add_co_u32_e32 v4, vcc, 0x8080, v4
	s_nop 1
	v_addc_co_u32_e32 v5, vcc, 0, v5, vcc
	global_load_ushort v139, v[4:5], off
	v_add_co_u32_e32 v4, vcc, 0x8080, v4
	s_nop 1
	v_addc_co_u32_e32 v5, vcc, 0, v5, vcc
	global_load_ushort v140, v[4:5], off
	v_add_co_u32_e32 v4, vcc, 0x8080, v4
	s_nop 1
	v_addc_co_u32_e32 v5, vcc, 0, v5, vcc
	global_load_ushort v141, v[4:5], off
	v_add_co_u32_e32 v4, vcc, 0x8080, v4
	s_nop 1
	v_addc_co_u32_e32 v5, vcc, 0, v5, vcc
	global_load_ushort v142, v[4:5], off
	v_add_co_u32_e32 v4, vcc, 0x8080, v4
	s_nop 1
	v_addc_co_u32_e32 v5, vcc, 0, v5, vcc
	global_load_ushort v143, v[4:5], off
	v_add_co_u32_e32 v4, vcc, 0x8080, v4
	s_nop 1
	v_addc_co_u32_e32 v5, vcc, 0, v5, vcc
	global_load_ushort v144, v[4:5], off
	v_add_co_u32_e32 v4, vcc, 0x8080, v4
	s_nop 1
	v_addc_co_u32_e32 v5, vcc, 0, v5, vcc
; DI float bf2f(u16 v) { return __uint_as_float(((unsigned)v) << 16); }
; DI void phase_mixc(const Prm& p, unsigned char* smem_raw, int l, int& base) {
;     ...
;       for (int c = 0; c < 96; ++c) { const float v = bf2f(src[(size_t)c * TBP]); s += v; ss += v * v; }
	global_load_ushort v145, v[4:5], off
	v_add_co_u32_e32 v4, vcc, 0x8080, v4
	s_nop 1
	v_addc_co_u32_e32 v5, vcc, 0, v5, vcc
	global_load_ushort v146, v[4:5], off
	v_add_co_u32_e32 v4, vcc, 0x8080, v4
	s_nop 1
	v_addc_co_u32_e32 v5, vcc, 0, v5, vcc
	global_load_ushort v147, v[4:5], off
	v_add_co_u32_e32 v4, vcc, 0x8080, v4
	s_nop 1
	v_addc_co_u32_e32 v5, vcc, 0, v5, vcc
	global_load_ushort v148, v[4:5], off
	v_add_co_u32_e32 v4, vcc, 0x8080, v4
	s_nop 1
	v_addc_co_u32_e32 v5, vcc, 0, v5, vcc
	global_load_ushort v149, v[4:5], off
	v_add_co_u32_e32 v4, vcc, 0x8080, v4
	s_nop 1
	v_addc_co_u32_e32 v5, vcc, 0, v5, vcc
	global_load_ushort v150, v[4:5], off
	v_add_co_u32_e32 v4, vcc, 0x8080, v4
	s_nop 1
	v_addc_co_u32_e32 v5, vcc, 0, v5, vcc
	global_load_ushort v151, v[4:5], off
	v_add_co_u32_e32 v4, vcc, 0x8080, v4
	s_nop 1
	v_addc_co_u32_e32 v5, vcc, 0, v5, vcc
	global_load_ushort v152, v[4:5], off
	v_add_co_u32_e32 v4, vcc, 0x8080, v4
	s_nop 1
	v_addc_co_u32_e32 v5, vcc, 0, v5, vcc
	global_load_ushort v153, v[4:5], off
	v_add_co_u32_e32 v4, vcc, 0x8080, v4
	s_nop 1
	v_addc_co_u32_e32 v5, vcc, 0, v5, vcc
	global_load_ushort v154, v[4:5], off
	v_add_co_u32_e32 v4, vcc, 0x8080, v4
	s_nop 1
	v_addc_co_u32_e32 v5, vcc, 0, v5, vcc
	global_load_ushort v155, v[4:5], off
	v_add_co_u32_e32 v4, vcc, 0x8080, v4
	s_nop 1
	v_addc_co_u32_e32 v5, vcc, 0, v5, vcc
	global_load_ushort v156, v[4:5], off
	v_add_co_u32_e32 v4, vcc, 0x8080, v4
	s_nop 1
	v_addc_co_u32_e32 v5, vcc, 0, v5, vcc
	global_load_ushort v157, v[4:5], off
	v_add_co_u32_e32 v4, vcc, 0x8080, v4
	s_nop 1
	v_addc_co_u32_e32 v5, vcc, 0, v5, vcc
	global_load_ushort v158, v[4:5], off
	v_add_co_u32_e32 v4, vcc, 0x8080, v4
	s_nop 1
	v_addc_co_u32_e32 v5, vcc, 0, v5, vcc
	global_load_ushort v159, v[4:5], off
	v_add_co_u32_e32 v4, vcc, 0x8080, v4
	s_nop 1
	v_addc_co_u32_e32 v5, vcc, 0, v5, vcc
	global_load_ushort v160, v[4:5], off
	v_add_co_u32_e32 v4, vcc, 0x8080, v4
	s_nop 1
	v_addc_co_u32_e32 v5, vcc, 0, v5, vcc
	global_load_ushort v161, v[4:5], off
	v_add_co_u32_e32 v4, vcc, 0x8080, v4
	s_nop 1
	v_addc_co_u32_e32 v5, vcc, 0, v5, vcc
	global_load_ushort v162, v[4:5], off
	v_add_co_u32_e32 v4, vcc, 0x8080, v4
	s_nop 1
	v_addc_co_u32_e32 v5, vcc, 0, v5, vcc
	global_load_ushort v163, v[4:5], off
	v_add_co_u32_e32 v4, vcc, 0x8080, v4
	s_nop 1
	v_addc_co_u32_e32 v5, vcc, 0, v5, vcc
	global_load_ushort v164, v[4:5], off
	v_add_co_u32_e32 v4, vcc, 0x8080, v4
	s_nop 1
	v_addc_co_u32_e32 v5, vcc, 0, v5, vcc
	global_load_ushort v165, v[4:5], off
	v_add_co_u32_e32 v4, vcc, 0x8080, v4
	s_nop 1
	v_addc_co_u32_e32 v5, vcc, 0, v5, vcc
	global_load_ushort v166, v[4:5], off
	v_add_co_u32_e32 v4, vcc, 0x8080, v4
	s_nop 1
	v_addc_co_u32_e32 v5, vcc, 0, v5, vcc
	global_load_ushort v167, v[4:5], off
	v_add_co_u32_e32 v4, vcc, 0x8080, v4
	s_nop 1
	v_addc_co_u32_e32 v5, vcc, 0, v5, vcc
	global_load_ushort v168, v[4:5], off
	v_add_co_u32_e32 v4, vcc, 0x8080, v4
	s_nop 1
	v_addc_co_u32_e32 v5, vcc, 0, v5, vcc
	global_load_ushort v169, v[4:5], off
	v_add_co_u32_e32 v4, vcc, 0x8080, v4
	s_nop 1
	v_addc_co_u32_e32 v5, vcc, 0, v5, vcc
	global_load_ushort v170, v[4:5], off
	v_add_co_u32_e32 v4, vcc, 0x8080, v4
	s_nop 1
	v_addc_co_u32_e32 v5, vcc, 0, v5, vcc
	global_load_ushort v171, v[4:5], off
	v_add_co_u32_e32 v4, vcc, 0x8080, v4
	s_nop 1
	v_addc_co_u32_e32 v5, vcc, 0, v5, vcc
	global_load_ushort v172, v[4:5], off
	v_add_co_u32_e32 v4, vcc, 0x8080, v4
	s_nop 1
	v_addc_co_u32_e32 v5, vcc, 0, v5, vcc
	global_load_ushort v173, v[4:5], off
	v_add_co_u32_e32 v4, vcc, 0x8080, v4
	s_nop 1
	v_addc_co_u32_e32 v5, vcc, 0, v5, vcc
	global_load_ushort v174, v[4:5], off
	v_add_co_u32_e32 v4, vcc, 0x8080, v4
	s_nop 1
	v_addc_co_u32_e32 v5, vcc, 0, v5, vcc
	global_load_ushort v175, v[4:5], off
	v_add_co_u32_e32 v4, vcc, 0x8080, v4
	s_nop 1
	v_addc_co_u32_e32 v5, vcc, 0, v5, vcc
	global_load_ushort v176, v[4:5], off
	v_add_co_u32_e32 v4, vcc, 0x8080, v4
	s_nop 1
	v_addc_co_u32_e32 v5, vcc, 0, v5, vcc
	global_load_ushort v177, v[4:5], off
	v_add_co_u32_e32 v4, vcc, 0x8080, v4
	s_nop 1
	v_addc_co_u32_e32 v5, vcc, 0, v5, vcc
	global_load_ushort v178, v[4:5], off
	v_add_co_u32_e32 v4, vcc, 0x8080, v4
	s_nop 1
	v_addc_co_u32_e32 v5, vcc, 0, v5, vcc
	global_load_ushort v179, v[4:5], off
	v_add_co_u32_e32 v4, vcc, 0x8080, v4
	s_nop 1
	v_addc_co_u32_e32 v5, vcc, 0, v5, vcc
	global_load_ushort v180, v[4:5], off
	v_add_co_u32_e32 v4, vcc, 0x8080, v4
	s_nop 1
	v_addc_co_u32_e32 v5, vcc, 0, v5, vcc
	global_load_ushort v181, v[4:5], off
	v_add_co_u32_e32 v4, vcc, 0x8080, v4
	s_nop 1
	v_addc_co_u32_e32 v5, vcc, 0, v5, vcc
	global_load_ushort v182, v[4:5], off
	v_add_co_u32_e32 v4, vcc, 0x8080, v4
	s_nop 1
	v_addc_co_u32_e32 v5, vcc, 0, v5, vcc
	global_load_ushort v183, v[4:5], off
	v_add_co_u32_e32 v4, vcc, 0x8080, v4
	s_nop 1
	v_addc_co_u32_e32 v5, vcc, 0, v5, vcc
	global_load_ushort v184, v[4:5], off
	v_add_co_u32_e32 v4, vcc, 0x8080, v4
	s_nop 1
	v_addc_co_u32_e32 v5, vcc, 0, v5, vcc
	global_load_ushort v185, v[4:5], off
	v_add_co_u32_e32 v4, vcc, 0x8080, v4
	s_nop 1
	v_addc_co_u32_e32 v5, vcc, 0, v5, vcc
	global_load_ushort v186, v[4:5], off
	v_add_co_u32_e32 v4, vcc, 0x8080, v4
	s_nop 1
	v_addc_co_u32_e32 v5, vcc, 0, v5, vcc
	global_load_ushort v187, v[4:5], off
	v_add_co_u32_e32 v4, vcc, 0x8080, v4
	s_nop 1
	v_addc_co_u32_e32 v5, vcc, 0, v5, vcc
	global_load_ushort v188, v[4:5], off
	v_add_co_u32_e32 v4, vcc, 0x8080, v4
	s_nop 1
	v_addc_co_u32_e32 v5, vcc, 0, v5, vcc
	global_load_ushort v189, v[4:5], off
	v_add_co_u32_e32 v4, vcc, 0x8080, v4
	s_nop 1
	v_addc_co_u32_e32 v5, vcc, 0, v5, vcc
	global_load_ushort v190, v[4:5], off
	v_add_co_u32_e32 v4, vcc, 0x8080, v4
	s_nop 1
	v_addc_co_u32_e32 v5, vcc, 0, v5, vcc
	global_load_ushort v191, v[4:5], off
	v_add_co_u32_e32 v4, vcc, 0x8080, v4
	s_nop 1
	v_addc_co_u32_e32 v5, vcc, 0, v5, vcc
	global_load_ushort v192, v[4:5], off
	v_add_co_u32_e32 v4, vcc, 0x8080, v4
	s_nop 1
	v_addc_co_u32_e32 v5, vcc, 0, v5, vcc
	global_load_ushort v193, v[4:5], off
	v_add_co_u32_e32 v4, vcc, 0x8080, v4
	s_nop 1
	v_addc_co_u32_e32 v5, vcc, 0, v5, vcc
	global_load_ushort v194, v[4:5], off
	v_add_co_u32_e32 v4, vcc, 0x8080, v4
	s_nop 1
	v_addc_co_u32_e32 v5, vcc, 0, v5, vcc
	global_load_ushort v195, v[4:5], off
	s_waitcnt vmcnt(63)
; DI float bf2f(u16 v) { return __uint_as_float(((unsigned)v) << 16); }
; DI void phase_mixc(const Prm& p, unsigned char* smem_raw, int l, int& base) {
;     ...
;       for (int c = 0; c < 96; ++c) { const float v = bf2f(src[(size_t)c * TBP]); s += v; ss += v * v; }
	v_lshlrev_b32_e32 v8, 16, v100
	v_mul_f32_e32 v9, v8, v8
	v_pk_add_f32 v[6:7], v[6:7], v[8:9]
	v_lshlrev_b32_e32 v8, 16, v101
	v_mul_f32_e32 v9, v8, v8
	v_pk_add_f32 v[6:7], v[6:7], v[8:9]
	v_lshlrev_b32_e32 v8, 16, v102
	v_mul_f32_e32 v9, v8, v8
	v_pk_add_f32 v[6:7], v[6:7], v[8:9]
	v_lshlrev_b32_e32 v8, 16, v103
	v_mul_f32_e32 v9, v8, v8
	v_pk_add_f32 v[6:7], v[6:7], v[8:9]
	v_lshlrev_b32_e32 v8, 16, v104
	v_mul_f32_e32 v9, v8, v8
	v_pk_add_f32 v[6:7], v[6:7], v[8:9]
	v_lshlrev_b32_e32 v8, 16, v105
	v_mul_f32_e32 v9, v8, v8
	v_pk_add_f32 v[6:7], v[6:7], v[8:9]
	v_lshlrev_b32_e32 v8, 16, v106
	v_mul_f32_e32 v9, v8, v8
	v_pk_add_f32 v[6:7], v[6:7], v[8:9]
	v_lshlrev_b32_e32 v8, 16, v107
	v_mul_f32_e32 v9, v8, v8
	v_pk_add_f32 v[6:7], v[6:7], v[8:9]
	s_waitcnt vmcnt(63)
	v_lshlrev_b32_e32 v8, 16, v108
	v_mul_f32_e32 v9, v8, v8
	v_pk_add_f32 v[6:7], v[6:7], v[8:9]
	v_lshlrev_b32_e32 v8, 16, v109
	v_mul_f32_e32 v9, v8, v8
	v_pk_add_f32 v[6:7], v[6:7], v[8:9]
	v_lshlrev_b32_e32 v8, 16, v110
	v_mul_f32_e32 v9, v8, v8
	v_pk_add_f32 v[6:7], v[6:7], v[8:9]
	v_lshlrev_b32_e32 v8, 16, v111
	v_mul_f32_e32 v9, v8, v8
	v_pk_add_f32 v[6:7], v[6:7], v[8:9]
	v_lshlrev_b32_e32 v8, 16, v112
	v_mul_f32_e32 v9, v8, v8
	v_pk_add_f32 v[6:7], v[6:7], v[8:9]
	v_lshlrev_b32_e32 v8, 16, v113
	v_mul_f32_e32 v9, v8, v8
	v_pk_add_f32 v[6:7], v[6:7], v[8:9]
	v_lshlrev_b32_e32 v8, 16, v114
	v_mul_f32_e32 v9, v8, v8
	v_pk_add_f32 v[6:7], v[6:7], v[8:9]
	v_lshlrev_b32_e32 v8, 16, v115
	v_mul_f32_e32 v9, v8, v8
	v_pk_add_f32 v[6:7], v[6:7], v[8:9]
	s_waitcnt vmcnt(63)
	v_lshlrev_b32_e32 v8, 16, v116
	v_mul_f32_e32 v9, v8, v8
	v_pk_add_f32 v[6:7], v[6:7], v[8:9]
	v_lshlrev_b32_e32 v8, 16, v117
	v_mul_f32_e32 v9, v8, v8
	v_pk_add_f32 v[6:7], v[6:7], v[8:9]
	v_lshlrev_b32_e32 v8, 16, v118
	v_mul_f32_e32 v9, v8, v8
	v_pk_add_f32 v[6:7], v[6:7], v[8:9]
	v_lshlrev_b32_e32 v8, 16, v119
	v_mul_f32_e32 v9, v8, v8
	v_pk_add_f32 v[6:7], v[6:7], v[8:9]
	v_lshlrev_b32_e32 v8, 16, v120
	v_mul_f32_e32 v9, v8, v8
	v_pk_add_f32 v[6:7], v[6:7], v[8:9]
	v_lshlrev_b32_e32 v8, 16, v121
	v_mul_f32_e32 v9, v8, v8
	v_pk_add_f32 v[6:7], v[6:7], v[8:9]
	v_lshlrev_b32_e32 v8, 16, v122
	v_mul_f32_e32 v9, v8, v8
	v_pk_add_f32 v[6:7], v[6:7], v[8:9]
	v_lshlrev_b32_e32 v8, 16, v123
	v_mul_f32_e32 v9, v8, v8
	v_pk_add_f32 v[6:7], v[6:7], v[8:9]
	s_waitcnt vmcnt(63)
	v_lshlrev_b32_e32 v8, 16, v124
	v_mul_f32_e32 v9, v8, v8
	v_pk_add_f32 v[6:7], v[6:7], v[8:9]
	v_lshlrev_b32_e32 v8, 16, v125
	v_mul_f32_e32 v9, v8, v8
	v_pk_add_f32 v[6:7], v[6:7], v[8:9]
	v_lshlrev_b32_e32 v8, 16, v126
	v_mul_f32_e32 v9, v8, v8
	v_pk_add_f32 v[6:7], v[6:7], v[8:9]
	v_lshlrev_b32_e32 v8, 16, v127
	v_mul_f32_e32 v9, v8, v8
	v_pk_add_f32 v[6:7], v[6:7], v[8:9]
	v_lshlrev_b32_e32 v8, 16, v128
	v_mul_f32_e32 v9, v8, v8
	v_pk_add_f32 v[6:7], v[6:7], v[8:9]
	v_lshlrev_b32_e32 v8, 16, v129
	v_mul_f32_e32 v9, v8, v8
	v_pk_add_f32 v[6:7], v[6:7], v[8:9]
	v_lshlrev_b32_e32 v8, 16, v130
	v_mul_f32_e32 v9, v8, v8
	v_pk_add_f32 v[6:7], v[6:7], v[8:9]
	v_lshlrev_b32_e32 v8, 16, v131
	v_mul_f32_e32 v9, v8, v8
	v_pk_add_f32 v[6:7], v[6:7], v[8:9]
	s_waitcnt vmcnt(56)
	v_lshlrev_b32_e32 v8, 16, v132
	v_mul_f32_e32 v9, v8, v8
	v_pk_add_f32 v[6:7], v[6:7], v[8:9]
	v_lshlrev_b32_e32 v8, 16, v133
	v_mul_f32_e32 v9, v8, v8
	v_pk_add_f32 v[6:7], v[6:7], v[8:9]
	v_lshlrev_b32_e32 v8, 16, v134
	v_mul_f32_e32 v9, v8, v8
	v_pk_add_f32 v[6:7], v[6:7], v[8:9]
	v_lshlrev_b32_e32 v8, 16, v135
	v_mul_f32_e32 v9, v8, v8
	v_pk_add_f32 v[6:7], v[6:7], v[8:9]
	v_lshlrev_b32_e32 v8, 16, v136
	v_mul_f32_e32 v9, v8, v8
	v_pk_add_f32 v[6:7], v[6:7], v[8:9]
	v_lshlrev_b32_e32 v8, 16, v137
	v_mul_f32_e32 v9, v8, v8
	v_pk_add_f32 v[6:7], v[6:7], v[8:9]
	v_lshlrev_b32_e32 v8, 16, v138
	v_mul_f32_e32 v9, v8, v8
	v_pk_add_f32 v[6:7], v[6:7], v[8:9]
	v_lshlrev_b32_e32 v8, 16, v139
	v_mul_f32_e32 v9, v8, v8
	v_pk_add_f32 v[6:7], v[6:7], v[8:9]
	s_waitcnt vmcnt(48)
	v_lshlrev_b32_e32 v8, 16, v140
	v_mul_f32_e32 v9, v8, v8
	v_pk_add_f32 v[6:7], v[6:7], v[8:9]
	v_lshlrev_b32_e32 v8, 16, v141
	v_mul_f32_e32 v9, v8, v8
	v_pk_add_f32 v[6:7], v[6:7], v[8:9]
	v_lshlrev_b32_e32 v8, 16, v142
	v_mul_f32_e32 v9, v8, v8
	v_pk_add_f32 v[6:7], v[6:7], v[8:9]
	v_lshlrev_b32_e32 v8, 16, v143
	v_mul_f32_e32 v9, v8, v8
	v_pk_add_f32 v[6:7], v[6:7], v[8:9]
	v_lshlrev_b32_e32 v8, 16, v144
	v_mul_f32_e32 v9, v8, v8
	v_pk_add_f32 v[6:7], v[6:7], v[8:9]
	v_lshlrev_b32_e32 v8, 16, v145
	v_mul_f32_e32 v9, v8, v8
	v_pk_add_f32 v[6:7], v[6:7], v[8:9]
	v_lshlrev_b32_e32 v8, 16, v146
	v_mul_f32_e32 v9, v8, v8
	v_pk_add_f32 v[6:7], v[6:7], v[8:9]
	v_lshlrev_b32_e32 v8, 16, v147
	v_mul_f32_e32 v9, v8, v8
	v_pk_add_f32 v[6:7], v[6:7], v[8:9]
	s_waitcnt vmcnt(40)
	v_lshlrev_b32_e32 v8, 16, v148
	v_mul_f32_e32 v9, v8, v8
	v_pk_add_f32 v[6:7], v[6:7], v[8:9]
	v_lshlrev_b32_e32 v8, 16, v149
	v_mul_f32_e32 v9, v8, v8
	v_pk_add_f32 v[6:7], v[6:7], v[8:9]
	v_lshlrev_b32_e32 v8, 16, v150
	v_mul_f32_e32 v9, v8, v8
	v_pk_add_f32 v[6:7], v[6:7], v[8:9]
	v_lshlrev_b32_e32 v8, 16, v151
	v_mul_f32_e32 v9, v8, v8
	v_pk_add_f32 v[6:7], v[6:7], v[8:9]
	v_lshlrev_b32_e32 v8, 16, v152
	v_mul_f32_e32 v9, v8, v8
	v_pk_add_f32 v[6:7], v[6:7], v[8:9]
	v_lshlrev_b32_e32 v8, 16, v153
	v_mul_f32_e32 v9, v8, v8
	v_pk_add_f32 v[6:7], v[6:7], v[8:9]
	v_lshlrev_b32_e32 v8, 16, v154
	v_mul_f32_e32 v9, v8, v8
	v_pk_add_f32 v[6:7], v[6:7], v[8:9]
	v_lshlrev_b32_e32 v8, 16, v155
	v_mul_f32_e32 v9, v8, v8
	v_pk_add_f32 v[6:7], v[6:7], v[8:9]
	s_waitcnt vmcnt(32)
; DI float bf2f(u16 v) { return __uint_as_float(((unsigned)v) << 16); }
; DI void phase_mixc(const Prm& p, unsigned char* smem_raw, int l, int& base) {
;     ...
;       for (int c = 0; c < 96; ++c) { const float v = bf2f(src[(size_t)c * TBP]); s += v; ss += v * v; }
;       red[qf * 256 + q * 2] = s; red[qf * 256 + q * 2 + 1] = ss;
;       __syncthreads();
;       if (tid < 128) {
;         const float s1 = red[q * 2] + red[256 + q * 2] + red[512 + q * 2] + red[768 + q * 2];
;         const float s2 = red[q * 2 + 1] + red[256 + q * 2 + 1] + red[512 + q * 2 + 1] + red[768 + q * 2 + 1];
;         const float mu = s1 * (1.f / 384.f);
;         const float var = fmaxf(s2 * (1.f / 384.f) - mu * mu, 0.f);
;         st[q] = mu; st[128 + q] = rsqrtf(var + 1e-6f);
;       }
	v_lshlrev_b32_e32 v8, 16, v156
	v_mul_f32_e32 v9, v8, v8
	v_pk_add_f32 v[6:7], v[6:7], v[8:9]
	v_lshlrev_b32_e32 v8, 16, v157
	v_mul_f32_e32 v9, v8, v8
	v_pk_add_f32 v[6:7], v[6:7], v[8:9]
	v_lshlrev_b32_e32 v8, 16, v158
	v_mul_f32_e32 v9, v8, v8
	v_pk_add_f32 v[6:7], v[6:7], v[8:9]
	v_lshlrev_b32_e32 v8, 16, v159
	v_mul_f32_e32 v9, v8, v8
	v_pk_add_f32 v[6:7], v[6:7], v[8:9]
	v_lshlrev_b32_e32 v8, 16, v160
	v_mul_f32_e32 v9, v8, v8
	v_pk_add_f32 v[6:7], v[6:7], v[8:9]
	v_lshlrev_b32_e32 v8, 16, v161
	v_mul_f32_e32 v9, v8, v8
	v_pk_add_f32 v[6:7], v[6:7], v[8:9]
	v_lshlrev_b32_e32 v8, 16, v162
	v_mul_f32_e32 v9, v8, v8
	v_pk_add_f32 v[6:7], v[6:7], v[8:9]
	v_lshlrev_b32_e32 v8, 16, v163
	v_mul_f32_e32 v9, v8, v8
	v_pk_add_f32 v[6:7], v[6:7], v[8:9]
	s_waitcnt vmcnt(24)
	v_lshlrev_b32_e32 v8, 16, v164
	v_mul_f32_e32 v9, v8, v8
	v_pk_add_f32 v[6:7], v[6:7], v[8:9]
	v_lshlrev_b32_e32 v8, 16, v165
	v_mul_f32_e32 v9, v8, v8
	v_pk_add_f32 v[6:7], v[6:7], v[8:9]
	v_lshlrev_b32_e32 v8, 16, v166
	v_mul_f32_e32 v9, v8, v8
	v_pk_add_f32 v[6:7], v[6:7], v[8:9]
	v_lshlrev_b32_e32 v8, 16, v167
	v_mul_f32_e32 v9, v8, v8
	v_pk_add_f32 v[6:7], v[6:7], v[8:9]
	v_lshlrev_b32_e32 v8, 16, v168
	v_mul_f32_e32 v9, v8, v8
	v_pk_add_f32 v[6:7], v[6:7], v[8:9]
	v_lshlrev_b32_e32 v8, 16, v169
	v_mul_f32_e32 v9, v8, v8
	v_pk_add_f32 v[6:7], v[6:7], v[8:9]
	v_lshlrev_b32_e32 v8, 16, v170
	v_mul_f32_e32 v9, v8, v8
	v_pk_add_f32 v[6:7], v[6:7], v[8:9]
	v_lshlrev_b32_e32 v8, 16, v171
	v_mul_f32_e32 v9, v8, v8
	v_pk_add_f32 v[6:7], v[6:7], v[8:9]
	s_waitcnt vmcnt(16)
	v_lshlrev_b32_e32 v8, 16, v172
	v_mul_f32_e32 v9, v8, v8
	v_pk_add_f32 v[6:7], v[6:7], v[8:9]
	v_lshlrev_b32_e32 v8, 16, v173
	v_mul_f32_e32 v9, v8, v8
	v_pk_add_f32 v[6:7], v[6:7], v[8:9]
	v_lshlrev_b32_e32 v8, 16, v174
	v_mul_f32_e32 v9, v8, v8
	v_pk_add_f32 v[6:7], v[6:7], v[8:9]
	v_lshlrev_b32_e32 v8, 16, v175
	v_mul_f32_e32 v9, v8, v8
	v_pk_add_f32 v[6:7], v[6:7], v[8:9]
	v_lshlrev_b32_e32 v8, 16, v176
	v_mul_f32_e32 v9, v8, v8
	v_pk_add_f32 v[6:7], v[6:7], v[8:9]
	v_lshlrev_b32_e32 v8, 16, v177
	v_mul_f32_e32 v9, v8, v8
	v_pk_add_f32 v[6:7], v[6:7], v[8:9]
	v_lshlrev_b32_e32 v8, 16, v178
	v_mul_f32_e32 v9, v8, v8
	v_pk_add_f32 v[6:7], v[6:7], v[8:9]
	v_lshlrev_b32_e32 v8, 16, v179
	v_mul_f32_e32 v9, v8, v8
	v_pk_add_f32 v[6:7], v[6:7], v[8:9]
	s_waitcnt vmcnt(8)
	v_lshlrev_b32_e32 v8, 16, v180
	v_mul_f32_e32 v9, v8, v8
	v_pk_add_f32 v[6:7], v[6:7], v[8:9]
	v_lshlrev_b32_e32 v8, 16, v181
	v_mul_f32_e32 v9, v8, v8
	v_pk_add_f32 v[6:7], v[6:7], v[8:9]
	v_lshlrev_b32_e32 v8, 16, v182
	v_mul_f32_e32 v9, v8, v8
	v_pk_add_f32 v[6:7], v[6:7], v[8:9]
	v_lshlrev_b32_e32 v8, 16, v183
	v_mul_f32_e32 v9, v8, v8
	v_pk_add_f32 v[6:7], v[6:7], v[8:9]
	v_lshlrev_b32_e32 v8, 16, v184
	v_mul_f32_e32 v9, v8, v8
	v_pk_add_f32 v[6:7], v[6:7], v[8:9]
	v_lshlrev_b32_e32 v8, 16, v185
	v_mul_f32_e32 v9, v8, v8
	v_pk_add_f32 v[6:7], v[6:7], v[8:9]
	v_lshlrev_b32_e32 v8, 16, v186
	v_mul_f32_e32 v9, v8, v8
	v_pk_add_f32 v[6:7], v[6:7], v[8:9]
	v_lshlrev_b32_e32 v8, 16, v187
	v_mul_f32_e32 v9, v8, v8
	v_pk_add_f32 v[6:7], v[6:7], v[8:9]
	s_waitcnt vmcnt(0)
	v_lshlrev_b32_e32 v8, 16, v188
	v_mul_f32_e32 v9, v8, v8
	v_pk_add_f32 v[6:7], v[6:7], v[8:9]
	v_lshlrev_b32_e32 v8, 16, v189
	v_mul_f32_e32 v9, v8, v8
	v_pk_add_f32 v[6:7], v[6:7], v[8:9]
	v_lshlrev_b32_e32 v8, 16, v190
	v_mul_f32_e32 v9, v8, v8
	v_pk_add_f32 v[6:7], v[6:7], v[8:9]
	v_lshlrev_b32_e32 v8, 16, v191
	v_mul_f32_e32 v9, v8, v8
	v_pk_add_f32 v[6:7], v[6:7], v[8:9]
	v_lshlrev_b32_e32 v8, 16, v192
	v_mul_f32_e32 v9, v8, v8
	v_pk_add_f32 v[6:7], v[6:7], v[8:9]
	v_lshlrev_b32_e32 v8, 16, v193
	v_mul_f32_e32 v9, v8, v8
	v_pk_add_f32 v[6:7], v[6:7], v[8:9]
	v_lshlrev_b32_e32 v8, 16, v194
	v_mul_f32_e32 v9, v8, v8
	v_pk_add_f32 v[6:7], v[6:7], v[8:9]
	v_lshlrev_b32_e32 v8, 16, v195
	v_mul_f32_e32 v9, v8, v8
	v_pk_add_f32 v[6:7], v[6:7], v[8:9]
	ds_write_b64 v59, v[6:7]
	s_waitcnt lgkmcnt(0)
	s_barrier
	s_and_saveexec_b64 s[2:3], s[0:1]
	s_cbranch_execz .LBB0_2006
	ds_read2st64_b64 v[2:5], v58 offset1:2
	s_mov_b32 s4, 0x3b2aaaab
	s_waitcnt lgkmcnt(0)
	v_pk_add_f32 v[6:7], v[2:3], v[4:5]
	ds_read2st64_b64 v[2:5], v58 offset0:4 offset1:6
	s_waitcnt lgkmcnt(0)
	v_pk_add_f32 v[2:3], v[6:7], v[2:3]
	s_nop 0
	v_pk_add_f32 v[2:3], v[2:3], v[4:5]
	s_nop 0
	v_pk_mul_f32 v[2:3], v[2:3], s[4:5] op_sel_hi:[1,0]
	s_nop 0
	v_fma_f32 v0, -v2, v2, v3
	v_max_f32_e32 v0, 0, v0
	v_add_f32_e32 v0, 0x358637bd, v0
	v_cmp_gt_f32_e32 vcc, s85, v0
	v_mul_f32_e32 v3, 0x4b800000, v0
	s_nop 0
	v_cndmask_b32_e32 v0, v0, v3, vcc
	v_rsq_f32_e32 v0, v0
	s_nop 0
	v_mul_f32_e32 v3, 0x45800000, v0
	v_cndmask_b32_e32 v0, v0, v3, vcc
	ds_write2st64_b32 v60, v2, v0 offset1:2
